# E_MO/E_DOWN epilogues: all H loads issued up front, counted vmcnt waits, batched sumsq reduction
# speedup vs baseline: 1.0158x; 1.0158x over previous
.LBB0_902:
	s_and_b64 vcc, exec, s[2:3]
	s_cbranch_vccz .LBB0_920
	v_ashrrev_i32_e32 v149, 31, v148
	v_add_u32_e32 v134, v132, v167
	v_ashrrev_i32_e32 v135, 31, v134
	v_lshlrev_b64 v[250:251], 11, v[148:149]
	v_lshl_add_u64 v[250:251], s[46:47], 0, v[250:251]
	v_lshl_add_u64 v[250:251], v[134:135], 1, v[250:251]
	v_lshl_add_u64 v[252:253], v[148:149], 2, s[42:43]
	v_xor_b32_e32 v132, 16, v230
	v_xor_b32_e32 v133, 32, v230
	v_lshlrev_b32_e32 v132, 2, v132
	v_lshlrev_b32_e32 v133, 2, v133
	v_mov_b64_e32 v[248:249], v[250:251]
	global_load_dwordx4 v[196:199], v[248:249], off
	global_load_dwordx4 v[200:203], v[248:249], off offset:256
	s_mov_b64 s[2:3], 0x8000
	v_lshl_add_u64 v[248:249], v[248:249], 0, s[2:3]
	global_load_dwordx4 v[204:207], v[248:249], off
	global_load_dwordx4 v[208:211], v[248:249], off offset:256
	v_lshl_add_u64 v[248:249], v[248:249], 0, s[2:3]
	global_load_dwordx4 v[212:215], v[248:249], off
	global_load_dwordx4 v[216:219], v[248:249], off offset:256
	v_lshl_add_u64 v[248:249], v[248:249], 0, s[2:3]
	global_load_dwordx4 v[220:223], v[248:249], off
	global_load_dwordx4 v[224:227], v[248:249], off offset:256
	s_mov_b64 s[2:3], 0x28000
	v_lshl_add_u64 v[248:249], v[248:249], 0, s[2:3]
	global_load_dwordx4 v[232:235], v[248:249], off
	global_load_dwordx4 v[236:239], v[248:249], off offset:256
	s_mov_b64 s[2:3], 0x8000
	v_lshl_add_u64 v[248:249], v[248:249], 0, s[2:3]
	global_load_dwordx4 v[240:243], v[248:249], off
	global_load_dwordx4 v[244:247], v[248:249], off offset:256
	v_lshl_add_u64 v[248:249], v[248:249], 0, s[2:3]
	global_load_dwordx4 v[148:151], v[248:249], off
	global_load_dwordx4 v[152:155], v[248:249], off offset:256
	v_lshl_add_u64 v[248:249], v[248:249], 0, s[2:3]
	global_load_dwordx4 v[156:159], v[248:249], off
	global_load_dwordx4 v[160:163], v[248:249], off offset:256
	s_waitcnt vmcnt(14)
	v_lshlrev_b32_e32 v134, 16, v196
	v_and_b32_e32 v135, 0xffff0000, v196
	v_pk_add_f32 v[128:129], v[128:129], v[134:135]
	v_lshlrev_b32_e32 v196, 16, v197
	v_and_b32_e32 v197, 0xffff0000, v197
	v_pk_add_f32 v[130:131], v[130:131], v[196:197]
	v_lshlrev_b32_e32 v134, 16, v198
	v_and_b32_e32 v135, 0xffff0000, v198
	v_pk_add_f32 v[124:125], v[124:125], v[134:135]
	v_lshlrev_b32_e32 v198, 16, v199
	v_and_b32_e32 v199, 0xffff0000, v199
	v_pk_add_f32 v[126:127], v[126:127], v[198:199]
	v_lshlrev_b32_e32 v134, 16, v200
	v_and_b32_e32 v135, 0xffff0000, v200
	v_pk_add_f32 v[120:121], v[120:121], v[134:135]
	v_lshlrev_b32_e32 v200, 16, v201
	v_and_b32_e32 v201, 0xffff0000, v201
	v_pk_add_f32 v[122:123], v[122:123], v[200:201]
	v_lshlrev_b32_e32 v134, 16, v202
	v_and_b32_e32 v135, 0xffff0000, v202
	v_pk_add_f32 v[116:117], v[116:117], v[134:135]
	v_lshlrev_b32_e32 v202, 16, v203
	v_and_b32_e32 v203, 0xffff0000, v203
	v_pk_add_f32 v[118:119], v[118:119], v[202:203]
	v_mul_f32_e32 v196, v129, v129
	v_mul_f32_e32 v197, v131, v131
	v_fmac_f32_e32 v196, v128, v128
	v_fmac_f32_e32 v197, v130, v130
	v_mul_f32_e32 v198, v125, v125
	v_mul_f32_e32 v199, v127, v127
	v_add_f32_e32 v196, v196, v197
	v_fmac_f32_e32 v198, v124, v124
	v_fmac_f32_e32 v199, v126, v126
	v_cvt_pk_bf16_f32 v128, v128, v129
	v_add_f32_e32 v198, v198, v199
	v_cvt_pk_bf16_f32 v129, v130, v131
	v_add_f32_e32 v196, v196, v198
	v_cvt_pk_bf16_f32 v130, v124, v125
	v_cvt_pk_bf16_f32 v131, v126, v127
	global_store_dwordx4 v[250:251], v[128:131], off
	v_mul_f32_e32 v200, v121, v121
	v_mul_f32_e32 v201, v123, v123
	v_fmac_f32_e32 v200, v120, v120
	v_fmac_f32_e32 v201, v122, v122
	v_mul_f32_e32 v202, v117, v117
	v_mul_f32_e32 v203, v119, v119
	v_add_f32_e32 v200, v200, v201
	v_fmac_f32_e32 v202, v116, v116
	v_fmac_f32_e32 v203, v118, v118
	v_cvt_pk_bf16_f32 v120, v120, v121
	v_add_f32_e32 v202, v202, v203
	v_cvt_pk_bf16_f32 v121, v122, v123
	v_add_f32_e32 v200, v200, v202
	v_cvt_pk_bf16_f32 v122, v116, v117
	v_cvt_pk_bf16_f32 v123, v118, v119
	global_store_dwordx4 v[250:251], v[120:123], off offset:256
	v_add_f32_e32 v124, v196, v200
	v_lshl_add_u64 v[250:251], v[250:251], 0, s[2:3]
	s_waitcnt vmcnt(14)
	v_lshlrev_b32_e32 v134, 16, v204
	v_and_b32_e32 v135, 0xffff0000, v204
	v_pk_add_f32 v[108:109], v[108:109], v[134:135]
	v_lshlrev_b32_e32 v204, 16, v205
	v_and_b32_e32 v205, 0xffff0000, v205
	v_pk_add_f32 v[110:111], v[110:111], v[204:205]
	v_lshlrev_b32_e32 v134, 16, v206
	v_and_b32_e32 v135, 0xffff0000, v206
	v_pk_add_f32 v[100:101], v[100:101], v[134:135]
	v_lshlrev_b32_e32 v206, 16, v207
	v_and_b32_e32 v207, 0xffff0000, v207
	v_pk_add_f32 v[102:103], v[102:103], v[206:207]
	v_lshlrev_b32_e32 v134, 16, v208
	v_and_b32_e32 v135, 0xffff0000, v208
	v_pk_add_f32 v[112:113], v[112:113], v[134:135]
	v_lshlrev_b32_e32 v208, 16, v209
	v_and_b32_e32 v209, 0xffff0000, v209
	v_pk_add_f32 v[114:115], v[114:115], v[208:209]
	v_lshlrev_b32_e32 v134, 16, v210
	v_and_b32_e32 v135, 0xffff0000, v210
	v_pk_add_f32 v[104:105], v[104:105], v[134:135]
	v_lshlrev_b32_e32 v210, 16, v211
	v_and_b32_e32 v211, 0xffff0000, v211
	v_pk_add_f32 v[106:107], v[106:107], v[210:211]
	v_mul_f32_e32 v204, v109, v109
	v_mul_f32_e32 v205, v111, v111
	v_fmac_f32_e32 v204, v108, v108
	v_fmac_f32_e32 v205, v110, v110
	v_mul_f32_e32 v206, v101, v101
	v_mul_f32_e32 v207, v103, v103
	v_add_f32_e32 v204, v204, v205
	v_fmac_f32_e32 v206, v100, v100
	v_fmac_f32_e32 v207, v102, v102
	v_cvt_pk_bf16_f32 v108, v108, v109
	v_add_f32_e32 v206, v206, v207
	v_cvt_pk_bf16_f32 v109, v110, v111
	v_add_f32_e32 v204, v204, v206
	v_cvt_pk_bf16_f32 v110, v100, v101
	v_cvt_pk_bf16_f32 v111, v102, v103
	global_store_dwordx4 v[250:251], v[108:111], off
	v_mul_f32_e32 v208, v113, v113
	v_mul_f32_e32 v209, v115, v115
	v_fmac_f32_e32 v208, v112, v112
	v_fmac_f32_e32 v209, v114, v114
	v_mul_f32_e32 v210, v105, v105
	v_mul_f32_e32 v211, v107, v107
	v_add_f32_e32 v208, v208, v209
	v_fmac_f32_e32 v210, v104, v104
	v_fmac_f32_e32 v211, v106, v106
	v_cvt_pk_bf16_f32 v112, v112, v113
	v_add_f32_e32 v210, v210, v211
	v_cvt_pk_bf16_f32 v113, v114, v115
	v_add_f32_e32 v208, v208, v210
	v_cvt_pk_bf16_f32 v114, v104, v105
	v_cvt_pk_bf16_f32 v115, v106, v107
	global_store_dwordx4 v[250:251], v[112:115], off offset:256
	v_add_f32_e32 v100, v204, v208
	v_lshl_add_u64 v[250:251], v[250:251], 0, s[2:3]
	s_waitcnt vmcnt(14)
	v_lshlrev_b32_e32 v134, 16, v212
	v_and_b32_e32 v135, 0xffff0000, v212
	v_pk_add_f32 v[88:89], v[88:89], v[134:135]
	v_lshlrev_b32_e32 v212, 16, v213
	v_and_b32_e32 v213, 0xffff0000, v213
	v_pk_add_f32 v[90:91], v[90:91], v[212:213]
	v_lshlrev_b32_e32 v134, 16, v214
	v_and_b32_e32 v135, 0xffff0000, v214
	v_pk_add_f32 v[84:85], v[84:85], v[134:135]
	v_lshlrev_b32_e32 v214, 16, v215
	v_and_b32_e32 v215, 0xffff0000, v215
	v_pk_add_f32 v[86:87], v[86:87], v[214:215]
	v_lshlrev_b32_e32 v134, 16, v216
	v_and_b32_e32 v135, 0xffff0000, v216
	v_pk_add_f32 v[96:97], v[96:97], v[134:135]
	v_lshlrev_b32_e32 v216, 16, v217
	v_and_b32_e32 v217, 0xffff0000, v217
	v_pk_add_f32 v[98:99], v[98:99], v[216:217]
	v_lshlrev_b32_e32 v134, 16, v218
	v_and_b32_e32 v135, 0xffff0000, v218
	v_pk_add_f32 v[92:93], v[92:93], v[134:135]
	v_lshlrev_b32_e32 v218, 16, v219
	v_and_b32_e32 v219, 0xffff0000, v219
	v_pk_add_f32 v[94:95], v[94:95], v[218:219]
	v_mul_f32_e32 v212, v89, v89
	v_mul_f32_e32 v213, v91, v91
	v_fmac_f32_e32 v212, v88, v88
	v_fmac_f32_e32 v213, v90, v90
	v_mul_f32_e32 v214, v85, v85
	v_mul_f32_e32 v215, v87, v87
	v_add_f32_e32 v212, v212, v213
	v_fmac_f32_e32 v214, v84, v84
	v_fmac_f32_e32 v215, v86, v86
	v_cvt_pk_bf16_f32 v88, v88, v89
	v_add_f32_e32 v214, v214, v215
	v_cvt_pk_bf16_f32 v89, v90, v91
	v_add_f32_e32 v212, v212, v214
	v_cvt_pk_bf16_f32 v90, v84, v85
	v_cvt_pk_bf16_f32 v91, v86, v87
	global_store_dwordx4 v[250:251], v[88:91], off
	v_mul_f32_e32 v216, v97, v97
	v_mul_f32_e32 v217, v99, v99
	v_fmac_f32_e32 v216, v96, v96
	v_fmac_f32_e32 v217, v98, v98
	v_mul_f32_e32 v218, v93, v93
	v_mul_f32_e32 v219, v95, v95
	v_add_f32_e32 v216, v216, v217
	v_fmac_f32_e32 v218, v92, v92
	v_fmac_f32_e32 v219, v94, v94
	v_cvt_pk_bf16_f32 v96, v96, v97
	v_add_f32_e32 v218, v218, v219
	v_cvt_pk_bf16_f32 v97, v98, v99
	v_add_f32_e32 v216, v216, v218
	v_cvt_pk_bf16_f32 v98, v92, v93
	v_cvt_pk_bf16_f32 v99, v94, v95
	global_store_dwordx4 v[250:251], v[96:99], off offset:256
	v_add_f32_e32 v84, v212, v216
	v_lshl_add_u64 v[250:251], v[250:251], 0, s[2:3]
	s_waitcnt vmcnt(14)
	v_lshlrev_b32_e32 v134, 16, v220
	v_and_b32_e32 v135, 0xffff0000, v220
	v_pk_add_f32 v[56:57], v[56:57], v[134:135]
	v_lshlrev_b32_e32 v220, 16, v221
	v_and_b32_e32 v221, 0xffff0000, v221
	v_pk_add_f32 v[58:59], v[58:59], v[220:221]
	v_lshlrev_b32_e32 v134, 16, v222
	v_and_b32_e32 v135, 0xffff0000, v222
	v_pk_add_f32 v[44:45], v[44:45], v[134:135]
	v_lshlrev_b32_e32 v222, 16, v223
	v_and_b32_e32 v223, 0xffff0000, v223
	v_pk_add_f32 v[46:47], v[46:47], v[222:223]
	v_lshlrev_b32_e32 v134, 16, v224
	v_and_b32_e32 v135, 0xffff0000, v224
	v_pk_add_f32 v[80:81], v[80:81], v[134:135]
	v_lshlrev_b32_e32 v224, 16, v225
	v_and_b32_e32 v225, 0xffff0000, v225
	v_pk_add_f32 v[82:83], v[82:83], v[224:225]
	v_lshlrev_b32_e32 v134, 16, v226
	v_and_b32_e32 v135, 0xffff0000, v226
	v_pk_add_f32 v[76:77], v[76:77], v[134:135]
	v_lshlrev_b32_e32 v226, 16, v227
	v_and_b32_e32 v227, 0xffff0000, v227
	v_pk_add_f32 v[78:79], v[78:79], v[226:227]
	v_mul_f32_e32 v220, v57, v57
	v_mul_f32_e32 v221, v59, v59
	v_fmac_f32_e32 v220, v56, v56
	v_fmac_f32_e32 v221, v58, v58
	v_mul_f32_e32 v222, v45, v45
	v_mul_f32_e32 v223, v47, v47
	v_add_f32_e32 v220, v220, v221
	v_fmac_f32_e32 v222, v44, v44
	v_fmac_f32_e32 v223, v46, v46
	v_cvt_pk_bf16_f32 v56, v56, v57
	v_add_f32_e32 v222, v222, v223
	v_cvt_pk_bf16_f32 v57, v58, v59
	v_add_f32_e32 v220, v220, v222
	v_cvt_pk_bf16_f32 v58, v44, v45
	v_cvt_pk_bf16_f32 v59, v46, v47
	global_store_dwordx4 v[250:251], v[56:59], off
	v_mul_f32_e32 v224, v81, v81
	v_mul_f32_e32 v225, v83, v83
	v_fmac_f32_e32 v224, v80, v80
	v_fmac_f32_e32 v225, v82, v82
	v_mul_f32_e32 v226, v77, v77
	v_mul_f32_e32 v227, v79, v79
	v_add_f32_e32 v224, v224, v225
	v_fmac_f32_e32 v226, v76, v76
	v_fmac_f32_e32 v227, v78, v78
	v_cvt_pk_bf16_f32 v80, v80, v81
	v_add_f32_e32 v226, v226, v227
	v_cvt_pk_bf16_f32 v81, v82, v83
	v_add_f32_e32 v224, v224, v226
	v_cvt_pk_bf16_f32 v82, v76, v77
	v_cvt_pk_bf16_f32 v83, v78, v79
	global_store_dwordx4 v[250:251], v[80:83], off offset:256
	v_add_f32_e32 v44, v220, v224
	s_mov_b64 s[2:3], 0x28000
	v_lshl_add_u64 v[250:251], v[250:251], 0, s[2:3]
	s_waitcnt vmcnt(14)
	v_lshlrev_b32_e32 v134, 16, v232
	v_and_b32_e32 v135, 0xffff0000, v232
	v_pk_add_f32 v[64:65], v[64:65], v[134:135]
	v_lshlrev_b32_e32 v232, 16, v233
	v_and_b32_e32 v233, 0xffff0000, v233
	v_pk_add_f32 v[66:67], v[66:67], v[232:233]
	v_lshlrev_b32_e32 v134, 16, v234
	v_and_b32_e32 v135, 0xffff0000, v234
	v_pk_add_f32 v[60:61], v[60:61], v[134:135]
	v_lshlrev_b32_e32 v234, 16, v235
	v_and_b32_e32 v235, 0xffff0000, v235
	v_pk_add_f32 v[62:63], v[62:63], v[234:235]
	v_lshlrev_b32_e32 v134, 16, v236
	v_and_b32_e32 v135, 0xffff0000, v236
	v_pk_add_f32 v[72:73], v[72:73], v[134:135]
	v_lshlrev_b32_e32 v236, 16, v237
	v_and_b32_e32 v237, 0xffff0000, v237
	v_pk_add_f32 v[74:75], v[74:75], v[236:237]
	v_lshlrev_b32_e32 v134, 16, v238
	v_and_b32_e32 v135, 0xffff0000, v238
	v_pk_add_f32 v[68:69], v[68:69], v[134:135]
	v_lshlrev_b32_e32 v238, 16, v239
	v_and_b32_e32 v239, 0xffff0000, v239
	v_pk_add_f32 v[70:71], v[70:71], v[238:239]
	v_mul_f32_e32 v232, v65, v65
	v_mul_f32_e32 v233, v67, v67
	v_fmac_f32_e32 v232, v64, v64
	v_fmac_f32_e32 v233, v66, v66
	v_mul_f32_e32 v234, v61, v61
	v_mul_f32_e32 v235, v63, v63
	v_add_f32_e32 v232, v232, v233
	v_fmac_f32_e32 v234, v60, v60
	v_fmac_f32_e32 v235, v62, v62
	v_cvt_pk_bf16_f32 v64, v64, v65
	v_add_f32_e32 v234, v234, v235
	v_cvt_pk_bf16_f32 v65, v66, v67
	v_add_f32_e32 v232, v232, v234
	v_cvt_pk_bf16_f32 v66, v60, v61
	v_cvt_pk_bf16_f32 v67, v62, v63
	global_store_dwordx4 v[250:251], v[64:67], off
	v_mul_f32_e32 v236, v73, v73
	v_mul_f32_e32 v237, v75, v75
	v_fmac_f32_e32 v236, v72, v72
	v_fmac_f32_e32 v237, v74, v74
	v_mul_f32_e32 v238, v69, v69
	v_mul_f32_e32 v239, v71, v71
	v_add_f32_e32 v236, v236, v237
	v_fmac_f32_e32 v238, v68, v68
	v_fmac_f32_e32 v239, v70, v70
	v_cvt_pk_bf16_f32 v72, v72, v73
	v_add_f32_e32 v238, v238, v239
	v_cvt_pk_bf16_f32 v73, v74, v75
	v_add_f32_e32 v236, v236, v238
	v_cvt_pk_bf16_f32 v74, v68, v69
	v_cvt_pk_bf16_f32 v75, v70, v71
	global_store_dwordx4 v[250:251], v[72:75], off offset:256
	v_add_f32_e32 v60, v232, v236
	s_mov_b64 s[2:3], 0x8000
	v_lshl_add_u64 v[250:251], v[250:251], 0, s[2:3]
	s_waitcnt vmcnt(14)
	v_lshlrev_b32_e32 v134, 16, v240
	v_and_b32_e32 v135, 0xffff0000, v240
	v_pk_add_f32 v[40:41], v[40:41], v[134:135]
	v_lshlrev_b32_e32 v240, 16, v241
	v_and_b32_e32 v241, 0xffff0000, v241
	v_pk_add_f32 v[42:43], v[42:43], v[240:241]
	v_lshlrev_b32_e32 v134, 16, v242
	v_and_b32_e32 v135, 0xffff0000, v242
	v_pk_add_f32 v[36:37], v[36:37], v[134:135]
	v_lshlrev_b32_e32 v242, 16, v243
	v_and_b32_e32 v243, 0xffff0000, v243
	v_pk_add_f32 v[38:39], v[38:39], v[242:243]
	v_lshlrev_b32_e32 v134, 16, v244
	v_and_b32_e32 v135, 0xffff0000, v244
	v_pk_add_f32 v[52:53], v[52:53], v[134:135]
	v_lshlrev_b32_e32 v244, 16, v245
	v_and_b32_e32 v245, 0xffff0000, v245
	v_pk_add_f32 v[54:55], v[54:55], v[244:245]
	v_lshlrev_b32_e32 v134, 16, v246
	v_and_b32_e32 v135, 0xffff0000, v246
	v_pk_add_f32 v[48:49], v[48:49], v[134:135]
	v_lshlrev_b32_e32 v246, 16, v247
	v_and_b32_e32 v247, 0xffff0000, v247
	v_pk_add_f32 v[50:51], v[50:51], v[246:247]
	v_mul_f32_e32 v240, v41, v41
	v_mul_f32_e32 v241, v43, v43
	v_fmac_f32_e32 v240, v40, v40
	v_fmac_f32_e32 v241, v42, v42
	v_mul_f32_e32 v242, v37, v37
	v_mul_f32_e32 v243, v39, v39
	v_add_f32_e32 v240, v240, v241
	v_fmac_f32_e32 v242, v36, v36
	v_fmac_f32_e32 v243, v38, v38
	v_cvt_pk_bf16_f32 v40, v40, v41
	v_add_f32_e32 v242, v242, v243
	v_cvt_pk_bf16_f32 v41, v42, v43
	v_add_f32_e32 v240, v240, v242
	v_cvt_pk_bf16_f32 v42, v36, v37
	v_cvt_pk_bf16_f32 v43, v38, v39
	global_store_dwordx4 v[250:251], v[40:43], off
	v_mul_f32_e32 v244, v53, v53
	v_mul_f32_e32 v245, v55, v55
	v_fmac_f32_e32 v244, v52, v52
	v_fmac_f32_e32 v245, v54, v54
	v_mul_f32_e32 v246, v49, v49
	v_mul_f32_e32 v247, v51, v51
	v_add_f32_e32 v244, v244, v245
	v_fmac_f32_e32 v246, v48, v48
	v_fmac_f32_e32 v247, v50, v50
	v_cvt_pk_bf16_f32 v52, v52, v53
	v_add_f32_e32 v246, v246, v247
	v_cvt_pk_bf16_f32 v53, v54, v55
	v_add_f32_e32 v244, v244, v246
	v_cvt_pk_bf16_f32 v54, v48, v49
	v_cvt_pk_bf16_f32 v55, v50, v51
	global_store_dwordx4 v[250:251], v[52:55], off offset:256
	v_add_f32_e32 v36, v240, v244
	v_lshl_add_u64 v[250:251], v[250:251], 0, s[2:3]
	s_waitcnt vmcnt(14)
	v_lshlrev_b32_e32 v134, 16, v148
	v_and_b32_e32 v135, 0xffff0000, v148
	v_pk_add_f32 v[22:23], v[22:23], v[134:135]
	v_lshlrev_b32_e32 v148, 16, v149
	v_and_b32_e32 v149, 0xffff0000, v149
	v_pk_add_f32 v[24:25], v[24:25], v[148:149]
	v_lshlrev_b32_e32 v134, 16, v150
	v_and_b32_e32 v135, 0xffff0000, v150
	v_pk_add_f32 v[18:19], v[18:19], v[134:135]
	v_lshlrev_b32_e32 v150, 16, v151
	v_and_b32_e32 v151, 0xffff0000, v151
	v_pk_add_f32 v[20:21], v[20:21], v[150:151]
	v_lshlrev_b32_e32 v134, 16, v152
	v_and_b32_e32 v135, 0xffff0000, v152
	v_pk_add_f32 v[32:33], v[32:33], v[134:135]
	v_lshlrev_b32_e32 v152, 16, v153
	v_and_b32_e32 v153, 0xffff0000, v153
	v_pk_add_f32 v[34:35], v[34:35], v[152:153]
	v_lshlrev_b32_e32 v134, 16, v154
	v_and_b32_e32 v135, 0xffff0000, v154
	v_pk_add_f32 v[28:29], v[28:29], v[134:135]
	v_lshlrev_b32_e32 v154, 16, v155
	v_and_b32_e32 v155, 0xffff0000, v155
	v_pk_add_f32 v[30:31], v[30:31], v[154:155]
	v_mul_f32_e32 v148, v23, v23
	v_mul_f32_e32 v149, v25, v25
	v_fmac_f32_e32 v148, v22, v22
	v_fmac_f32_e32 v149, v24, v24
	v_mul_f32_e32 v150, v19, v19
	v_mul_f32_e32 v151, v21, v21
	v_add_f32_e32 v148, v148, v149
	v_fmac_f32_e32 v150, v18, v18
	v_fmac_f32_e32 v151, v20, v20
	v_cvt_pk_bf16_f32 v22, v22, v23
	v_add_f32_e32 v150, v150, v151
	v_cvt_pk_bf16_f32 v23, v24, v25
	v_add_f32_e32 v148, v148, v150
	v_cvt_pk_bf16_f32 v24, v18, v19
	v_cvt_pk_bf16_f32 v25, v20, v21
	global_store_dwordx4 v[250:251], v[22:25], off
	v_mul_f32_e32 v152, v33, v33
	v_mul_f32_e32 v153, v35, v35
	v_fmac_f32_e32 v152, v32, v32
	v_fmac_f32_e32 v153, v34, v34
	v_mul_f32_e32 v154, v29, v29
	v_mul_f32_e32 v155, v31, v31
	v_add_f32_e32 v152, v152, v153
	v_fmac_f32_e32 v154, v28, v28
	v_fmac_f32_e32 v155, v30, v30
	v_cvt_pk_bf16_f32 v32, v32, v33
	v_add_f32_e32 v154, v154, v155
	v_cvt_pk_bf16_f32 v33, v34, v35
	v_add_f32_e32 v152, v152, v154
	v_cvt_pk_bf16_f32 v34, v28, v29
	v_cvt_pk_bf16_f32 v35, v30, v31
	global_store_dwordx4 v[250:251], v[32:35], off offset:256
	v_add_f32_e32 v18, v148, v152
	v_lshl_add_u64 v[250:251], v[250:251], 0, s[2:3]
	s_waitcnt vmcnt(14)
	v_lshlrev_b32_e32 v134, 16, v156
	v_and_b32_e32 v135, 0xffff0000, v156
	v_pk_add_f32 v[6:7], v[6:7], v[134:135]
	v_lshlrev_b32_e32 v156, 16, v157
	v_and_b32_e32 v157, 0xffff0000, v157
	v_pk_add_f32 v[8:9], v[8:9], v[156:157]
	v_lshlrev_b32_e32 v134, 16, v158
	v_and_b32_e32 v135, 0xffff0000, v158
	v_pk_add_f32 v[2:3], v[2:3], v[134:135]
	v_lshlrev_b32_e32 v158, 16, v159
	v_and_b32_e32 v159, 0xffff0000, v159
	v_pk_add_f32 v[4:5], v[4:5], v[158:159]
	v_lshlrev_b32_e32 v134, 16, v160
	v_and_b32_e32 v135, 0xffff0000, v160
	v_pk_add_f32 v[14:15], v[14:15], v[134:135]
	v_lshlrev_b32_e32 v160, 16, v161
	v_and_b32_e32 v161, 0xffff0000, v161
	v_pk_add_f32 v[16:17], v[16:17], v[160:161]
	v_lshlrev_b32_e32 v134, 16, v162
	v_and_b32_e32 v135, 0xffff0000, v162
	v_pk_add_f32 v[10:11], v[10:11], v[134:135]
	v_lshlrev_b32_e32 v162, 16, v163
	v_and_b32_e32 v163, 0xffff0000, v163
	v_pk_add_f32 v[12:13], v[12:13], v[162:163]
	v_mul_f32_e32 v156, v7, v7
	v_mul_f32_e32 v157, v9, v9
	v_fmac_f32_e32 v156, v6, v6
	v_fmac_f32_e32 v157, v8, v8
	v_mul_f32_e32 v158, v3, v3
	v_mul_f32_e32 v159, v5, v5
	v_add_f32_e32 v156, v156, v157
	v_fmac_f32_e32 v158, v2, v2
	v_fmac_f32_e32 v159, v4, v4
	v_cvt_pk_bf16_f32 v6, v6, v7
	v_add_f32_e32 v158, v158, v159
	v_cvt_pk_bf16_f32 v7, v8, v9
	v_add_f32_e32 v156, v156, v158
	v_cvt_pk_bf16_f32 v8, v2, v3
	v_cvt_pk_bf16_f32 v9, v4, v5
	global_store_dwordx4 v[250:251], v[6:9], off
	v_mul_f32_e32 v160, v15, v15
	v_mul_f32_e32 v161, v17, v17
	v_fmac_f32_e32 v160, v14, v14
	v_fmac_f32_e32 v161, v16, v16
	v_mul_f32_e32 v162, v11, v11
	v_mul_f32_e32 v163, v13, v13
	v_add_f32_e32 v160, v160, v161
	v_fmac_f32_e32 v162, v10, v10
	v_fmac_f32_e32 v163, v12, v12
	v_cvt_pk_bf16_f32 v14, v14, v15
	v_add_f32_e32 v162, v162, v163
	v_cvt_pk_bf16_f32 v15, v16, v17
	v_add_f32_e32 v160, v160, v162
	v_cvt_pk_bf16_f32 v16, v10, v11
	v_cvt_pk_bf16_f32 v17, v12, v13
	global_store_dwordx4 v[250:251], v[14:17], off offset:256
	v_add_f32_e32 v2, v156, v160
	ds_bpermute_b32 v125, v132, v124
	ds_bpermute_b32 v101, v132, v100
	ds_bpermute_b32 v85, v132, v84
	ds_bpermute_b32 v45, v132, v44
	ds_bpermute_b32 v61, v132, v60
	ds_bpermute_b32 v37, v132, v36
	ds_bpermute_b32 v19, v132, v18
	ds_bpermute_b32 v3, v132, v2
	s_waitcnt lgkmcnt(0)
	v_add_f32_e32 v124, v124, v125
	v_add_f32_e32 v100, v100, v101
	v_add_f32_e32 v84, v84, v85
	v_add_f32_e32 v44, v44, v45
	v_add_f32_e32 v60, v60, v61
	v_add_f32_e32 v36, v36, v37
	v_add_f32_e32 v18, v18, v19
	v_add_f32_e32 v2, v2, v3
	ds_bpermute_b32 v125, v133, v124
	ds_bpermute_b32 v101, v133, v100
	ds_bpermute_b32 v85, v133, v84
	ds_bpermute_b32 v45, v133, v44
	ds_bpermute_b32 v61, v133, v60
	ds_bpermute_b32 v37, v133, v36
	ds_bpermute_b32 v19, v133, v18
	ds_bpermute_b32 v3, v133, v2
	s_and_saveexec_b64 s[2:3], s[4:5]
	s_cbranch_execz .LBB0_919
	s_waitcnt lgkmcnt(0)
	v_add_f32_e32 v124, v124, v125
	v_add_f32_e32 v100, v100, v101
	v_add_f32_e32 v84, v84, v85
	v_add_f32_e32 v44, v44, v45
	v_add_f32_e32 v60, v60, v61
	v_add_f32_e32 v36, v36, v37
	v_add_f32_e32 v18, v18, v19
	v_add_f32_e32 v2, v2, v3
	global_atomic_add_f32 v[252:253], v124, off
	global_atomic_add_f32 v[252:253], v100, off offset:64
	global_atomic_add_f32 v[252:253], v84, off offset:128
	global_atomic_add_f32 v[252:253], v44, off offset:192
	global_atomic_add_f32 v[252:253], v60, off offset:512
	global_atomic_add_f32 v[252:253], v36, off offset:576
	global_atomic_add_f32 v[252:253], v18, off offset:640
	global_atomic_add_f32 v[252:253], v2, off offset:704

.LBB0_1042:
	v_add_u32_e32 v150, v132, v167
	s_and_b64 vcc, exec, s[76:77]
	v_ashrrev_i32_e32 v149, 31, v148
	v_ashrrev_i32_e32 v151, 31, v150
	s_cbranch_vccz .LBB0_1060
	v_lshlrev_b64 v[250:251], 11, v[148:149]
	v_lshl_add_u64 v[250:251], s[46:47], 0, v[250:251]
	v_lshl_add_u64 v[250:251], v[150:151], 1, v[250:251]
	v_lshl_add_u64 v[252:253], v[148:149], 2, s[58:59]
	v_xor_b32_e32 v132, 16, v230
	v_xor_b32_e32 v133, 32, v230
	v_lshlrev_b32_e32 v132, 2, v132
	v_lshlrev_b32_e32 v133, 2, v133
	v_mov_b64_e32 v[248:249], v[250:251]
	s_waitcnt lgkmcnt(0)
	global_load_dwordx4 v[196:199], v[248:249], off
	global_load_dwordx4 v[200:203], v[248:249], off offset:256
	s_mov_b64 s[0:1], 0x8000
	v_lshl_add_u64 v[248:249], v[248:249], 0, s[0:1]
	global_load_dwordx4 v[204:207], v[248:249], off
	global_load_dwordx4 v[208:211], v[248:249], off offset:256
	v_lshl_add_u64 v[248:249], v[248:249], 0, s[0:1]
	global_load_dwordx4 v[212:215], v[248:249], off
	global_load_dwordx4 v[216:219], v[248:249], off offset:256
	v_lshl_add_u64 v[248:249], v[248:249], 0, s[0:1]
	global_load_dwordx4 v[220:223], v[248:249], off
	global_load_dwordx4 v[224:227], v[248:249], off offset:256
	s_mov_b64 s[0:1], 0x28000
	v_lshl_add_u64 v[248:249], v[248:249], 0, s[0:1]
	global_load_dwordx4 v[232:235], v[248:249], off
	global_load_dwordx4 v[236:239], v[248:249], off offset:256
	s_mov_b64 s[0:1], 0x8000
	v_lshl_add_u64 v[248:249], v[248:249], 0, s[0:1]
	global_load_dwordx4 v[240:243], v[248:249], off
	global_load_dwordx4 v[244:247], v[248:249], off offset:256
	v_lshl_add_u64 v[248:249], v[248:249], 0, s[0:1]
	global_load_dwordx4 v[148:151], v[248:249], off
	global_load_dwordx4 v[152:155], v[248:249], off offset:256
	v_lshl_add_u64 v[248:249], v[248:249], 0, s[0:1]
	global_load_dwordx4 v[156:159], v[248:249], off
	global_load_dwordx4 v[160:163], v[248:249], off offset:256
	s_waitcnt vmcnt(14)
	v_lshlrev_b32_e32 v134, 16, v196
	v_and_b32_e32 v135, 0xffff0000, v196
	v_pk_add_f32 v[128:129], v[128:129], v[134:135]
	v_lshlrev_b32_e32 v196, 16, v197
	v_and_b32_e32 v197, 0xffff0000, v197
	v_pk_add_f32 v[130:131], v[130:131], v[196:197]
	v_lshlrev_b32_e32 v134, 16, v198
	v_and_b32_e32 v135, 0xffff0000, v198
	v_pk_add_f32 v[124:125], v[124:125], v[134:135]
	v_lshlrev_b32_e32 v198, 16, v199
	v_and_b32_e32 v199, 0xffff0000, v199
	v_pk_add_f32 v[126:127], v[126:127], v[198:199]
	v_lshlrev_b32_e32 v134, 16, v200
	v_and_b32_e32 v135, 0xffff0000, v200
	v_pk_add_f32 v[120:121], v[120:121], v[134:135]
	v_lshlrev_b32_e32 v200, 16, v201
	v_and_b32_e32 v201, 0xffff0000, v201
	v_pk_add_f32 v[122:123], v[122:123], v[200:201]
	v_lshlrev_b32_e32 v134, 16, v202
	v_and_b32_e32 v135, 0xffff0000, v202
	v_pk_add_f32 v[116:117], v[116:117], v[134:135]
	v_lshlrev_b32_e32 v202, 16, v203
	v_and_b32_e32 v203, 0xffff0000, v203
	v_pk_add_f32 v[118:119], v[118:119], v[202:203]
	v_mul_f32_e32 v196, v129, v129
	v_mul_f32_e32 v197, v131, v131
	v_fmac_f32_e32 v196, v128, v128
	v_fmac_f32_e32 v197, v130, v130
	v_mul_f32_e32 v198, v125, v125
	v_mul_f32_e32 v199, v127, v127
	v_add_f32_e32 v196, v196, v197
	v_fmac_f32_e32 v198, v124, v124
	v_fmac_f32_e32 v199, v126, v126
	v_cvt_pk_bf16_f32 v128, v128, v129
	v_add_f32_e32 v198, v198, v199
	v_cvt_pk_bf16_f32 v129, v130, v131
	v_add_f32_e32 v196, v196, v198
	v_cvt_pk_bf16_f32 v130, v124, v125
	v_cvt_pk_bf16_f32 v131, v126, v127
	global_store_dwordx4 v[250:251], v[128:131], off
	v_mul_f32_e32 v200, v121, v121
	v_mul_f32_e32 v201, v123, v123
	v_fmac_f32_e32 v200, v120, v120
	v_fmac_f32_e32 v201, v122, v122
	v_mul_f32_e32 v202, v117, v117
	v_mul_f32_e32 v203, v119, v119
	v_add_f32_e32 v200, v200, v201
	v_fmac_f32_e32 v202, v116, v116
	v_fmac_f32_e32 v203, v118, v118
	v_cvt_pk_bf16_f32 v120, v120, v121
	v_add_f32_e32 v202, v202, v203
	v_cvt_pk_bf16_f32 v121, v122, v123
	v_add_f32_e32 v200, v200, v202
	v_cvt_pk_bf16_f32 v122, v116, v117
	v_cvt_pk_bf16_f32 v123, v118, v119
	global_store_dwordx4 v[250:251], v[120:123], off offset:256
	v_add_f32_e32 v124, v196, v200
	v_lshl_add_u64 v[250:251], v[250:251], 0, s[0:1]
	s_waitcnt vmcnt(14)
	v_lshlrev_b32_e32 v134, 16, v204
	v_and_b32_e32 v135, 0xffff0000, v204
	v_pk_add_f32 v[108:109], v[108:109], v[134:135]
	v_lshlrev_b32_e32 v204, 16, v205
	v_and_b32_e32 v205, 0xffff0000, v205
	v_pk_add_f32 v[110:111], v[110:111], v[204:205]
	v_lshlrev_b32_e32 v134, 16, v206
	v_and_b32_e32 v135, 0xffff0000, v206
	v_pk_add_f32 v[100:101], v[100:101], v[134:135]
	v_lshlrev_b32_e32 v206, 16, v207
	v_and_b32_e32 v207, 0xffff0000, v207
	v_pk_add_f32 v[102:103], v[102:103], v[206:207]
	v_lshlrev_b32_e32 v134, 16, v208
	v_and_b32_e32 v135, 0xffff0000, v208
	v_pk_add_f32 v[112:113], v[112:113], v[134:135]
	v_lshlrev_b32_e32 v208, 16, v209
	v_and_b32_e32 v209, 0xffff0000, v209
	v_pk_add_f32 v[114:115], v[114:115], v[208:209]
	v_lshlrev_b32_e32 v134, 16, v210
	v_and_b32_e32 v135, 0xffff0000, v210
	v_pk_add_f32 v[104:105], v[104:105], v[134:135]
	v_lshlrev_b32_e32 v210, 16, v211
	v_and_b32_e32 v211, 0xffff0000, v211
	v_pk_add_f32 v[106:107], v[106:107], v[210:211]
	v_mul_f32_e32 v204, v109, v109
	v_mul_f32_e32 v205, v111, v111
	v_fmac_f32_e32 v204, v108, v108
	v_fmac_f32_e32 v205, v110, v110
	v_mul_f32_e32 v206, v101, v101
	v_mul_f32_e32 v207, v103, v103
	v_add_f32_e32 v204, v204, v205
	v_fmac_f32_e32 v206, v100, v100
	v_fmac_f32_e32 v207, v102, v102
	v_cvt_pk_bf16_f32 v108, v108, v109
	v_add_f32_e32 v206, v206, v207
	v_cvt_pk_bf16_f32 v109, v110, v111
	v_add_f32_e32 v204, v204, v206
	v_cvt_pk_bf16_f32 v110, v100, v101
	v_cvt_pk_bf16_f32 v111, v102, v103
	global_store_dwordx4 v[250:251], v[108:111], off
	v_mul_f32_e32 v208, v113, v113
	v_mul_f32_e32 v209, v115, v115
	v_fmac_f32_e32 v208, v112, v112
	v_fmac_f32_e32 v209, v114, v114
	v_mul_f32_e32 v210, v105, v105
	v_mul_f32_e32 v211, v107, v107
	v_add_f32_e32 v208, v208, v209
	v_fmac_f32_e32 v210, v104, v104
	v_fmac_f32_e32 v211, v106, v106
	v_cvt_pk_bf16_f32 v112, v112, v113
	v_add_f32_e32 v210, v210, v211
	v_cvt_pk_bf16_f32 v113, v114, v115
	v_add_f32_e32 v208, v208, v210
	v_cvt_pk_bf16_f32 v114, v104, v105
	v_cvt_pk_bf16_f32 v115, v106, v107
	global_store_dwordx4 v[250:251], v[112:115], off offset:256
	v_add_f32_e32 v100, v204, v208
	v_lshl_add_u64 v[250:251], v[250:251], 0, s[0:1]
	s_waitcnt vmcnt(14)
	v_lshlrev_b32_e32 v134, 16, v212
	v_and_b32_e32 v135, 0xffff0000, v212
	v_pk_add_f32 v[88:89], v[88:89], v[134:135]
	v_lshlrev_b32_e32 v212, 16, v213
	v_and_b32_e32 v213, 0xffff0000, v213
	v_pk_add_f32 v[90:91], v[90:91], v[212:213]
	v_lshlrev_b32_e32 v134, 16, v214
	v_and_b32_e32 v135, 0xffff0000, v214
	v_pk_add_f32 v[84:85], v[84:85], v[134:135]
	v_lshlrev_b32_e32 v214, 16, v215
	v_and_b32_e32 v215, 0xffff0000, v215
	v_pk_add_f32 v[86:87], v[86:87], v[214:215]
	v_lshlrev_b32_e32 v134, 16, v216
	v_and_b32_e32 v135, 0xffff0000, v216
	v_pk_add_f32 v[96:97], v[96:97], v[134:135]
	v_lshlrev_b32_e32 v216, 16, v217
	v_and_b32_e32 v217, 0xffff0000, v217
	v_pk_add_f32 v[98:99], v[98:99], v[216:217]
	v_lshlrev_b32_e32 v134, 16, v218
	v_and_b32_e32 v135, 0xffff0000, v218
	v_pk_add_f32 v[92:93], v[92:93], v[134:135]
	v_lshlrev_b32_e32 v218, 16, v219
	v_and_b32_e32 v219, 0xffff0000, v219
	v_pk_add_f32 v[94:95], v[94:95], v[218:219]
	v_mul_f32_e32 v212, v89, v89
	v_mul_f32_e32 v213, v91, v91
	v_fmac_f32_e32 v212, v88, v88
	v_fmac_f32_e32 v213, v90, v90
	v_mul_f32_e32 v214, v85, v85
	v_mul_f32_e32 v215, v87, v87
	v_add_f32_e32 v212, v212, v213
	v_fmac_f32_e32 v214, v84, v84
	v_fmac_f32_e32 v215, v86, v86
	v_cvt_pk_bf16_f32 v88, v88, v89
	v_add_f32_e32 v214, v214, v215
	v_cvt_pk_bf16_f32 v89, v90, v91
	v_add_f32_e32 v212, v212, v214
	v_cvt_pk_bf16_f32 v90, v84, v85
	v_cvt_pk_bf16_f32 v91, v86, v87
	global_store_dwordx4 v[250:251], v[88:91], off
	v_mul_f32_e32 v216, v97, v97
	v_mul_f32_e32 v217, v99, v99
	v_fmac_f32_e32 v216, v96, v96
	v_fmac_f32_e32 v217, v98, v98
	v_mul_f32_e32 v218, v93, v93
	v_mul_f32_e32 v219, v95, v95
	v_add_f32_e32 v216, v216, v217
	v_fmac_f32_e32 v218, v92, v92
	v_fmac_f32_e32 v219, v94, v94
	v_cvt_pk_bf16_f32 v96, v96, v97
	v_add_f32_e32 v218, v218, v219
	v_cvt_pk_bf16_f32 v97, v98, v99
	v_add_f32_e32 v216, v216, v218
	v_cvt_pk_bf16_f32 v98, v92, v93
	v_cvt_pk_bf16_f32 v99, v94, v95
	global_store_dwordx4 v[250:251], v[96:99], off offset:256
	v_add_f32_e32 v84, v212, v216
	v_lshl_add_u64 v[250:251], v[250:251], 0, s[0:1]
	s_waitcnt vmcnt(14)
	v_lshlrev_b32_e32 v134, 16, v220
	v_and_b32_e32 v135, 0xffff0000, v220
	v_pk_add_f32 v[56:57], v[56:57], v[134:135]
	v_lshlrev_b32_e32 v220, 16, v221
	v_and_b32_e32 v221, 0xffff0000, v221
	v_pk_add_f32 v[58:59], v[58:59], v[220:221]
	v_lshlrev_b32_e32 v134, 16, v222
	v_and_b32_e32 v135, 0xffff0000, v222
	v_pk_add_f32 v[44:45], v[44:45], v[134:135]
	v_lshlrev_b32_e32 v222, 16, v223
	v_and_b32_e32 v223, 0xffff0000, v223
	v_pk_add_f32 v[46:47], v[46:47], v[222:223]
	v_lshlrev_b32_e32 v134, 16, v224
	v_and_b32_e32 v135, 0xffff0000, v224
	v_pk_add_f32 v[80:81], v[80:81], v[134:135]
	v_lshlrev_b32_e32 v224, 16, v225
	v_and_b32_e32 v225, 0xffff0000, v225
	v_pk_add_f32 v[82:83], v[82:83], v[224:225]
	v_lshlrev_b32_e32 v134, 16, v226
	v_and_b32_e32 v135, 0xffff0000, v226
	v_pk_add_f32 v[76:77], v[76:77], v[134:135]
	v_lshlrev_b32_e32 v226, 16, v227
	v_and_b32_e32 v227, 0xffff0000, v227
	v_pk_add_f32 v[78:79], v[78:79], v[226:227]
	v_mul_f32_e32 v220, v57, v57
	v_mul_f32_e32 v221, v59, v59
	v_fmac_f32_e32 v220, v56, v56
	v_fmac_f32_e32 v221, v58, v58
	v_mul_f32_e32 v222, v45, v45
	v_mul_f32_e32 v223, v47, v47
	v_add_f32_e32 v220, v220, v221
	v_fmac_f32_e32 v222, v44, v44
	v_fmac_f32_e32 v223, v46, v46
	v_cvt_pk_bf16_f32 v56, v56, v57
	v_add_f32_e32 v222, v222, v223
	v_cvt_pk_bf16_f32 v57, v58, v59
	v_add_f32_e32 v220, v220, v222
	v_cvt_pk_bf16_f32 v58, v44, v45
	v_cvt_pk_bf16_f32 v59, v46, v47
	global_store_dwordx4 v[250:251], v[56:59], off
	v_mul_f32_e32 v224, v81, v81
	v_mul_f32_e32 v225, v83, v83
	v_fmac_f32_e32 v224, v80, v80
	v_fmac_f32_e32 v225, v82, v82
	v_mul_f32_e32 v226, v77, v77
	v_mul_f32_e32 v227, v79, v79
	v_add_f32_e32 v224, v224, v225
	v_fmac_f32_e32 v226, v76, v76
	v_fmac_f32_e32 v227, v78, v78
	v_cvt_pk_bf16_f32 v80, v80, v81
	v_add_f32_e32 v226, v226, v227
	v_cvt_pk_bf16_f32 v81, v82, v83
	v_add_f32_e32 v224, v224, v226
	v_cvt_pk_bf16_f32 v82, v76, v77
	v_cvt_pk_bf16_f32 v83, v78, v79
	global_store_dwordx4 v[250:251], v[80:83], off offset:256
	v_add_f32_e32 v44, v220, v224
	s_mov_b64 s[0:1], 0x28000
	v_lshl_add_u64 v[250:251], v[250:251], 0, s[0:1]
	s_waitcnt vmcnt(14)
	v_lshlrev_b32_e32 v134, 16, v232
	v_and_b32_e32 v135, 0xffff0000, v232
	v_pk_add_f32 v[64:65], v[64:65], v[134:135]
	v_lshlrev_b32_e32 v232, 16, v233
	v_and_b32_e32 v233, 0xffff0000, v233
	v_pk_add_f32 v[66:67], v[66:67], v[232:233]
	v_lshlrev_b32_e32 v134, 16, v234
	v_and_b32_e32 v135, 0xffff0000, v234
	v_pk_add_f32 v[60:61], v[60:61], v[134:135]
	v_lshlrev_b32_e32 v234, 16, v235
	v_and_b32_e32 v235, 0xffff0000, v235
	v_pk_add_f32 v[62:63], v[62:63], v[234:235]
	v_lshlrev_b32_e32 v134, 16, v236
	v_and_b32_e32 v135, 0xffff0000, v236
	v_pk_add_f32 v[72:73], v[72:73], v[134:135]
	v_lshlrev_b32_e32 v236, 16, v237
	v_and_b32_e32 v237, 0xffff0000, v237
	v_pk_add_f32 v[74:75], v[74:75], v[236:237]
	v_lshlrev_b32_e32 v134, 16, v238
	v_and_b32_e32 v135, 0xffff0000, v238
	v_pk_add_f32 v[68:69], v[68:69], v[134:135]
	v_lshlrev_b32_e32 v238, 16, v239
	v_and_b32_e32 v239, 0xffff0000, v239
	v_pk_add_f32 v[70:71], v[70:71], v[238:239]
	v_mul_f32_e32 v232, v65, v65
	v_mul_f32_e32 v233, v67, v67
	v_fmac_f32_e32 v232, v64, v64
	v_fmac_f32_e32 v233, v66, v66
	v_mul_f32_e32 v234, v61, v61
	v_mul_f32_e32 v235, v63, v63
	v_add_f32_e32 v232, v232, v233
	v_fmac_f32_e32 v234, v60, v60
	v_fmac_f32_e32 v235, v62, v62
	v_cvt_pk_bf16_f32 v64, v64, v65
	v_add_f32_e32 v234, v234, v235
	v_cvt_pk_bf16_f32 v65, v66, v67
	v_add_f32_e32 v232, v232, v234
	v_cvt_pk_bf16_f32 v66, v60, v61
	v_cvt_pk_bf16_f32 v67, v62, v63
	global_store_dwordx4 v[250:251], v[64:67], off
	v_mul_f32_e32 v236, v73, v73
	v_mul_f32_e32 v237, v75, v75
	v_fmac_f32_e32 v236, v72, v72
	v_fmac_f32_e32 v237, v74, v74
	v_mul_f32_e32 v238, v69, v69
	v_mul_f32_e32 v239, v71, v71
	v_add_f32_e32 v236, v236, v237
	v_fmac_f32_e32 v238, v68, v68
	v_fmac_f32_e32 v239, v70, v70
	v_cvt_pk_bf16_f32 v72, v72, v73
	v_add_f32_e32 v238, v238, v239
	v_cvt_pk_bf16_f32 v73, v74, v75
	v_add_f32_e32 v236, v236, v238
	v_cvt_pk_bf16_f32 v74, v68, v69
	v_cvt_pk_bf16_f32 v75, v70, v71
	global_store_dwordx4 v[250:251], v[72:75], off offset:256
	v_add_f32_e32 v60, v232, v236
	s_mov_b64 s[0:1], 0x8000
	v_lshl_add_u64 v[250:251], v[250:251], 0, s[0:1]
	s_waitcnt vmcnt(14)
	v_lshlrev_b32_e32 v134, 16, v240
	v_and_b32_e32 v135, 0xffff0000, v240
	v_pk_add_f32 v[40:41], v[40:41], v[134:135]
	v_lshlrev_b32_e32 v240, 16, v241
	v_and_b32_e32 v241, 0xffff0000, v241
	v_pk_add_f32 v[42:43], v[42:43], v[240:241]
	v_lshlrev_b32_e32 v134, 16, v242
	v_and_b32_e32 v135, 0xffff0000, v242
	v_pk_add_f32 v[36:37], v[36:37], v[134:135]
	v_lshlrev_b32_e32 v242, 16, v243
	v_and_b32_e32 v243, 0xffff0000, v243
	v_pk_add_f32 v[38:39], v[38:39], v[242:243]
	v_lshlrev_b32_e32 v134, 16, v244
	v_and_b32_e32 v135, 0xffff0000, v244
	v_pk_add_f32 v[52:53], v[52:53], v[134:135]
	v_lshlrev_b32_e32 v244, 16, v245
	v_and_b32_e32 v245, 0xffff0000, v245
	v_pk_add_f32 v[54:55], v[54:55], v[244:245]
	v_lshlrev_b32_e32 v134, 16, v246
	v_and_b32_e32 v135, 0xffff0000, v246
	v_pk_add_f32 v[48:49], v[48:49], v[134:135]
	v_lshlrev_b32_e32 v246, 16, v247
	v_and_b32_e32 v247, 0xffff0000, v247
	v_pk_add_f32 v[50:51], v[50:51], v[246:247]
	v_mul_f32_e32 v240, v41, v41
	v_mul_f32_e32 v241, v43, v43
	v_fmac_f32_e32 v240, v40, v40
	v_fmac_f32_e32 v241, v42, v42
	v_mul_f32_e32 v242, v37, v37
	v_mul_f32_e32 v243, v39, v39
	v_add_f32_e32 v240, v240, v241
	v_fmac_f32_e32 v242, v36, v36
	v_fmac_f32_e32 v243, v38, v38
	v_cvt_pk_bf16_f32 v40, v40, v41
	v_add_f32_e32 v242, v242, v243
	v_cvt_pk_bf16_f32 v41, v42, v43
	v_add_f32_e32 v240, v240, v242
	v_cvt_pk_bf16_f32 v42, v36, v37
	v_cvt_pk_bf16_f32 v43, v38, v39
	global_store_dwordx4 v[250:251], v[40:43], off
	v_mul_f32_e32 v244, v53, v53
	v_mul_f32_e32 v245, v55, v55
	v_fmac_f32_e32 v244, v52, v52
	v_fmac_f32_e32 v245, v54, v54
	v_mul_f32_e32 v246, v49, v49
	v_mul_f32_e32 v247, v51, v51
	v_add_f32_e32 v244, v244, v245
	v_fmac_f32_e32 v246, v48, v48
	v_fmac_f32_e32 v247, v50, v50
	v_cvt_pk_bf16_f32 v52, v52, v53
	v_add_f32_e32 v246, v246, v247
	v_cvt_pk_bf16_f32 v53, v54, v55
	v_add_f32_e32 v244, v244, v246
	v_cvt_pk_bf16_f32 v54, v48, v49
	v_cvt_pk_bf16_f32 v55, v50, v51
	global_store_dwordx4 v[250:251], v[52:55], off offset:256
	v_add_f32_e32 v36, v240, v244
	v_lshl_add_u64 v[250:251], v[250:251], 0, s[0:1]
	s_waitcnt vmcnt(14)
	v_lshlrev_b32_e32 v134, 16, v148
	v_and_b32_e32 v135, 0xffff0000, v148
	v_pk_add_f32 v[22:23], v[22:23], v[134:135]
	v_lshlrev_b32_e32 v148, 16, v149
	v_and_b32_e32 v149, 0xffff0000, v149
	v_pk_add_f32 v[24:25], v[24:25], v[148:149]
	v_lshlrev_b32_e32 v134, 16, v150
	v_and_b32_e32 v135, 0xffff0000, v150
	v_pk_add_f32 v[18:19], v[18:19], v[134:135]
	v_lshlrev_b32_e32 v150, 16, v151
	v_and_b32_e32 v151, 0xffff0000, v151
	v_pk_add_f32 v[20:21], v[20:21], v[150:151]
	v_lshlrev_b32_e32 v134, 16, v152
	v_and_b32_e32 v135, 0xffff0000, v152
	v_pk_add_f32 v[32:33], v[32:33], v[134:135]
	v_lshlrev_b32_e32 v152, 16, v153
	v_and_b32_e32 v153, 0xffff0000, v153
	v_pk_add_f32 v[34:35], v[34:35], v[152:153]
	v_lshlrev_b32_e32 v134, 16, v154
	v_and_b32_e32 v135, 0xffff0000, v154
	v_pk_add_f32 v[28:29], v[28:29], v[134:135]
	v_lshlrev_b32_e32 v154, 16, v155
	v_and_b32_e32 v155, 0xffff0000, v155
	v_pk_add_f32 v[30:31], v[30:31], v[154:155]
	v_mul_f32_e32 v148, v23, v23
	v_mul_f32_e32 v149, v25, v25
	v_fmac_f32_e32 v148, v22, v22
	v_fmac_f32_e32 v149, v24, v24
	v_mul_f32_e32 v150, v19, v19
	v_mul_f32_e32 v151, v21, v21
	v_add_f32_e32 v148, v148, v149
	v_fmac_f32_e32 v150, v18, v18
	v_fmac_f32_e32 v151, v20, v20
	v_cvt_pk_bf16_f32 v22, v22, v23
	v_add_f32_e32 v150, v150, v151
	v_cvt_pk_bf16_f32 v23, v24, v25
	v_add_f32_e32 v148, v148, v150
	v_cvt_pk_bf16_f32 v24, v18, v19
	v_cvt_pk_bf16_f32 v25, v20, v21
	global_store_dwordx4 v[250:251], v[22:25], off
	v_mul_f32_e32 v152, v33, v33
	v_mul_f32_e32 v153, v35, v35
	v_fmac_f32_e32 v152, v32, v32
	v_fmac_f32_e32 v153, v34, v34
	v_mul_f32_e32 v154, v29, v29
	v_mul_f32_e32 v155, v31, v31
	v_add_f32_e32 v152, v152, v153
	v_fmac_f32_e32 v154, v28, v28
	v_fmac_f32_e32 v155, v30, v30
	v_cvt_pk_bf16_f32 v32, v32, v33
	v_add_f32_e32 v154, v154, v155
	v_cvt_pk_bf16_f32 v33, v34, v35
	v_add_f32_e32 v152, v152, v154
	v_cvt_pk_bf16_f32 v34, v28, v29
	v_cvt_pk_bf16_f32 v35, v30, v31
	global_store_dwordx4 v[250:251], v[32:35], off offset:256
	v_add_f32_e32 v18, v148, v152
	v_lshl_add_u64 v[250:251], v[250:251], 0, s[0:1]
	s_waitcnt vmcnt(14)
	v_lshlrev_b32_e32 v134, 16, v156
	v_and_b32_e32 v135, 0xffff0000, v156
	v_pk_add_f32 v[6:7], v[6:7], v[134:135]
	v_lshlrev_b32_e32 v156, 16, v157
	v_and_b32_e32 v157, 0xffff0000, v157
	v_pk_add_f32 v[8:9], v[8:9], v[156:157]
	v_lshlrev_b32_e32 v134, 16, v158
	v_and_b32_e32 v135, 0xffff0000, v158
	v_pk_add_f32 v[2:3], v[2:3], v[134:135]
	v_lshlrev_b32_e32 v158, 16, v159
	v_and_b32_e32 v159, 0xffff0000, v159
	v_pk_add_f32 v[4:5], v[4:5], v[158:159]
	v_lshlrev_b32_e32 v134, 16, v160
	v_and_b32_e32 v135, 0xffff0000, v160
	v_pk_add_f32 v[14:15], v[14:15], v[134:135]
	v_lshlrev_b32_e32 v160, 16, v161
	v_and_b32_e32 v161, 0xffff0000, v161
	v_pk_add_f32 v[16:17], v[16:17], v[160:161]
	v_lshlrev_b32_e32 v134, 16, v162
	v_and_b32_e32 v135, 0xffff0000, v162
	v_pk_add_f32 v[10:11], v[10:11], v[134:135]
	v_lshlrev_b32_e32 v162, 16, v163
	v_and_b32_e32 v163, 0xffff0000, v163
	v_pk_add_f32 v[12:13], v[12:13], v[162:163]
	v_mul_f32_e32 v156, v7, v7
	v_mul_f32_e32 v157, v9, v9
	v_fmac_f32_e32 v156, v6, v6
	v_fmac_f32_e32 v157, v8, v8
	v_mul_f32_e32 v158, v3, v3
	v_mul_f32_e32 v159, v5, v5
	v_add_f32_e32 v156, v156, v157
	v_fmac_f32_e32 v158, v2, v2
	v_fmac_f32_e32 v159, v4, v4
	v_cvt_pk_bf16_f32 v6, v6, v7
	v_add_f32_e32 v158, v158, v159
	v_cvt_pk_bf16_f32 v7, v8, v9
	v_add_f32_e32 v156, v156, v158
	v_cvt_pk_bf16_f32 v8, v2, v3
	v_cvt_pk_bf16_f32 v9, v4, v5
	global_store_dwordx4 v[250:251], v[6:9], off
	v_mul_f32_e32 v160, v15, v15
	v_mul_f32_e32 v161, v17, v17
	v_fmac_f32_e32 v160, v14, v14
	v_fmac_f32_e32 v161, v16, v16
	v_mul_f32_e32 v162, v11, v11
	v_mul_f32_e32 v163, v13, v13
	v_add_f32_e32 v160, v160, v161
	v_fmac_f32_e32 v162, v10, v10
	v_fmac_f32_e32 v163, v12, v12
	v_cvt_pk_bf16_f32 v14, v14, v15
	v_add_f32_e32 v162, v162, v163
	v_cvt_pk_bf16_f32 v15, v16, v17
	v_add_f32_e32 v160, v160, v162
	v_cvt_pk_bf16_f32 v16, v10, v11
	v_cvt_pk_bf16_f32 v17, v12, v13
	global_store_dwordx4 v[250:251], v[14:17], off offset:256
	v_add_f32_e32 v2, v156, v160
	ds_bpermute_b32 v125, v132, v124
	ds_bpermute_b32 v101, v132, v100
	ds_bpermute_b32 v85, v132, v84
	ds_bpermute_b32 v45, v132, v44
	ds_bpermute_b32 v61, v132, v60
	ds_bpermute_b32 v37, v132, v36
	ds_bpermute_b32 v19, v132, v18
	ds_bpermute_b32 v3, v132, v2
	s_waitcnt lgkmcnt(0)
	v_add_f32_e32 v124, v124, v125
	v_add_f32_e32 v100, v100, v101
	v_add_f32_e32 v84, v84, v85
	v_add_f32_e32 v44, v44, v45
	v_add_f32_e32 v60, v60, v61
	v_add_f32_e32 v36, v36, v37
	v_add_f32_e32 v18, v18, v19
	v_add_f32_e32 v2, v2, v3
	ds_bpermute_b32 v125, v133, v124
	ds_bpermute_b32 v101, v133, v100
	ds_bpermute_b32 v85, v133, v84
	ds_bpermute_b32 v45, v133, v44
	ds_bpermute_b32 v61, v133, v60
	ds_bpermute_b32 v37, v133, v36
	ds_bpermute_b32 v19, v133, v18
	ds_bpermute_b32 v3, v133, v2
	s_and_saveexec_b64 s[0:1], s[4:5]
	s_cbranch_execz .LBB0_1059
	s_waitcnt lgkmcnt(0)
	v_add_f32_e32 v124, v124, v125
	v_add_f32_e32 v100, v100, v101
	v_add_f32_e32 v84, v84, v85
	v_add_f32_e32 v44, v44, v45
	v_add_f32_e32 v60, v60, v61
	v_add_f32_e32 v36, v36, v37
	v_add_f32_e32 v18, v18, v19
	v_add_f32_e32 v2, v2, v3
	global_atomic_add_f32 v[252:253], v124, off
	global_atomic_add_f32 v[252:253], v100, off offset:64
	global_atomic_add_f32 v[252:253], v84, off offset:128
	global_atomic_add_f32 v[252:253], v44, off offset:192
	global_atomic_add_f32 v[252:253], v60, off offset:512
	global_atomic_add_f32 v[252:253], v36, off offset:576
	global_atomic_add_f32 v[252:253], v18, off offset:640
	global_atomic_add_f32 v[252:253], v2, off offset:704
